# C loop: K/V tile staging by direct HBM-to-LDS loads (LDS-DMA) into unpadded XOR-swizzled LDS tiles; no staging VGPRs or ds_write in the loop; x3 unrolled
# speedup vs baseline: 1.0099x; 1.0049x over previous
; template <int MODE>
; DI void attn_unit(unsigned char* lds, const AttnParams& ap, int b, int h, int qb, int tid) {
;     ...
;   const int wave = tid >> 6, lane = tid & 63, r32 = lane & 31, hi = lane >> 5, bh = b * 4 + h;
;   constexpr int qcol0 = (MODE == 0) ? C_AQ : (MODE == 1) ? C_CQ : C_DQ, kcol0 = (MODE == 0) ? C_AK : (MODE == 1) ? C_CK : C_DK, ycol0 = (MODE == 0) ? 0 : (MODE == 1) ? 512 : 768;
;   const bf16_t* Vt = ap.Vt + (size_t)((MODE == 0) ? 0 : (MODE == 1) ? 2 : 3) * T_ * 256;
;   const size_t tokb = (size_t)b * SEQ;
;   const int qpos = qb * 256 + wave * 32 + r32, cw = qb * 4 + (wave >> 1);
;   bf16x8 qf[4];
;   { const bf16_t* qp = ap.P + (tokb + qpos) * PLD + qcol0 + h * 64 + 8 * hi;
; #pragma unroll
;     for (int ks = 0; ks < 4; ++ks) qf[ks] = *(const bf16x8*)(qp + 16 * ks); }
;   bf16_t* Ks0 = (bf16_t*)lds; bf16_t* Vs0 = Ks0 + NCH * 64 * 72; volatile int* flags = (volatile int*)(lds + 2 * NCH * 64 * 72 * 2);
;   const int jhi = 4 * qb + 3, jlo = (MODE == 0) ? ((4 * qb - 8 > 0) ? 4 * qb - 8 : 0) : 0, ntiles = jhi - jlo + 1;
;   const int lrow = tid >> 3, lch = tid & 7;
;   const bf16_t* kg = ap.P + (tokb + lrow) * PLD + kcol0 + h * 64 + 8 * lch;
;   const bf16_t* vg = Vt + (size_t)bh * 256 * 4096 + lrow * 64 + 8 * lch;
;   const int j0 = (MODE == 2) ? jhi : jlo;
;   u32x4 kreg[NCH], vreg[NCH];
; #pragma unroll
;   for (int c = 0; c < NCH; ++c) { const int jc = (MODE == 2) ? j0 - c : j0 + c; kreg[c] = *(const u32x4*)(kg + (size_t)jc * 64 * PLD); vreg[c] = *(const u32x4*)(vg + (size_t)jc * 4096); }
;   f32x16 O0[2], O1[2]; float l0 = 0.f, l1 = 0.f, cum = 0.f;
; #pragma unroll
;   for (int eb = 0; eb < 2; ++eb) { O0[eb] = splat16(0.f); O1[eb] = splat16(0.f); }
;   bool wdone = false;
;   if (MODE == 2 && D_EARLY) { if (tid < 8) flags[tid] = 0; }
;   for (int n = 0; n < ntiles; n += NCH) {
;     const int jb = (MODE == 2) ? jhi - n : jlo + n;
;     __syncthreads();
;     if (MODE == 2 && D_EARLY) { int alld = 1;
; #pragma unroll
;       for (int w = 0; w < 8; ++w) alld &= flags[w];
;       if (alld) break; }
; #pragma unroll
;     for (int c = 0; c < NCH; ++c) { *(u32x4*)(Ks0 + (c * 64 + lrow) * 72 + 8 * lch) = kreg[c]; *(u32x4*)(Vs0 + (c * 64 + lrow) * 72 + 8 * lch) = vreg[c]; }
;     __syncthreads();
;     if (n + NCH < ntiles) {
; #pragma unroll
.LBB0_845:
	v_readlane_b32 s0, v255, 51
	v_readlane_b32 s1, v255, 52
	s_andn2_saveexec_b64 s[6:7], s[0:1]
	s_cbranch_execz .LBB0_853
	v_mov_b32_e32 v1, v156
	v_readlane_b32 s0, v255, 25
	v_ashrrev_i32_e32 v2, 1, v1
	v_and_b32_e32 v2, 0xffffffe0, v2
	v_and_b32_e32 v7, 31, v1
	v_lshl_add_u32 v2, v0, 8, v2
	v_or_b32_e32 v2, v2, v7
	v_lshlrev_b32_e32 v32, 14, v4
	v_ashrrev_i32_e32 v3, 31, v2
	v_readlane_b32 s1, v255, 26
	v_lshl_add_u64 v[134:135], v[2:3], 0, v[32:33]
	v_bfe_u32 v47, v1, 5, 1
	v_mov_b64_e32 v[2:3], s[0:1]
	v_mad_u64_u32 v[8:9], s[0:1], v134, s82, v[2:3]
	v_mad_i32_i24 v9, v135, s82, v9
	v_lshlrev_b32_e32 v10, 7, v5
	v_mov_b32_e32 v11, v33
	v_lshl_add_u64 v[8:9], v[8:9], 0, v[10:11]
	v_lshlrev_b32_e32 v132, 4, v47
	v_mov_b32_e32 v133, v33
	v_lshl_add_u64 v[8:9], v[8:9], 0, v[132:133]
	v_ashrrev_i32_e32 v14, 3, v1
	global_load_dwordx4 v[112:115], v[8:9], off offset:3584
	global_load_dwordx4 v[42:45], v[8:9], off offset:3616
	global_load_dwordx4 v[38:41], v[8:9], off offset:3648
	global_load_dwordx4 v[34:37], v[8:9], off offset:3680
	v_add_u32_e32 v8, v14, v32
	v_mad_i64_i32 v[2:3], s[0:1], v8, s82, v[2:3]
	v_lshlrev_b32_e32 v8, 4, v1
	v_and_b32_e32 v32, 0x70, v8
	v_lshlrev_b32_e32 v8, 21, v5
	v_readlane_b32 s0, v255, 41
	v_lshl_add_u64 v[2:3], v[2:3], 0, v[10:11]
	v_lshl_or_b32 v8, v4, 23, v8
	v_mov_b32_e32 v9, v33
	v_readlane_b32 s1, v255, 42
	v_lshlrev_b32_e32 v12, 6, v14
	v_lshl_add_u64 v[2:3], v[2:3], 0, v[32:33]
	v_lshl_add_u64 v[10:11], s[0:1], 0, v[8:9]
	v_ashrrev_i32_e32 v13, 31, v12
	s_movk_i32 s0, 0x1000
	v_lshlrev_b64 v[12:13], 1, v[12:13]
	v_add_co_u32_e32 v2, vcc, s0, v2
	v_lshl_add_u64 v[10:11], v[10:11], 0, v[12:13]
	s_nop 0
	v_addc_co_u32_e32 v3, vcc, 0, v3, vcc
	v_lshl_add_u64 v[10:11], v[10:11], 0, v[32:33]
	global_load_dwordx4 v[120:123], v[2:3], off
	global_load_dwordx4 v[116:119], v[10:11], off
	v_ashrrev_i32_e32 v157, 7, v1
	v_lshlrev_b32_e32 v0, 2, v0
	v_mul_lo_u32 v1, v14, s68
	v_or_b32_e32 v12, v12, v32
	v_readlane_b32 s0, v255, 47
	v_add_u32_e32 v191, v157, v0
	v_add3_u32 v190, 0, v32, v1
	v_or_b32_e32 v192, 3, v0
	v_lshl_add_u64 v[0:1], v[12:13], 0, v[8:9]
	v_readlane_b32 s1, v255, 48
	v_add_u16_e32 v2, -1, v6
	v_and_b32_e32 v2, 3, v2
	v_lshl_add_u64 v[136:137], s[0:1], 0, v[0:1]
	v_mad_i64_i32 v[0:1], s[0:1], v14, s82, 0
	s_mov_b32 s0, 0x6880000
	s_nop 0
	v_mad_u64_u32 v[0:1], s[0:1], v4, s0, v[0:1]
	v_lshlrev_b32_e32 v2, 7, v2
	v_mov_b32_e32 v3, v33
	v_lshl_add_u64 v[0:1], v[0:1], 0, v[2:3]
	v_readlane_b32 s0, v255, 49
	v_lshl_add_u64 v[0:1], v[0:1], 0, v[32:33]
	v_readlane_b32 s1, v255, 50
	v_mov_b32_e32 v14, v33
	v_mov_b32_e32 v15, v33
	v_lshlrev_b32_e32 v46, 6, v5
	v_mul_u32_u24_e32 v155, 0x90, v7
	v_lshl_add_u64 v[138:139], s[0:1], 0, v[0:1]
	v_mov_b32_e32 v32, v33
	v_mov_b32_e32 v0, v33
	v_mov_b32_e32 v1, v33
	v_mov_b32_e32 v2, v33
	v_mov_b32_e32 v4, v33
	v_mov_b32_e32 v5, v33
	v_mov_b32_e32 v6, v33
	v_mov_b32_e32 v7, v33
	v_mov_b32_e32 v8, v33
	v_mov_b32_e32 v10, v33
	v_mov_b32_e32 v11, v33
	v_mov_b32_e32 v12, v33
	v_mov_b32_e32 v13, v33
	v_mov_b64_e32 v[78:79], v[14:15]
	v_mov_b64_e32 v[30:31], v[14:15]
	v_mov_b64_e32 v[94:95], v[14:15]
	s_mov_b32 s4, 0
	v_add_u32_e32 v133, 0, v132
	s_mov_b64 s[0:1], 0
	v_mov_b64_e32 v[76:77], v[12:13]
	v_mov_b64_e32 v[74:75], v[10:11]
	v_mov_b64_e32 v[72:73], v[8:9]
	v_mov_b64_e32 v[70:71], v[6:7]
	v_mov_b64_e32 v[68:69], v[4:5]
	v_mov_b64_e32 v[66:67], v[2:3]
	v_mov_b64_e32 v[64:65], v[0:1]
	v_mov_b64_e32 v[28:29], v[12:13]
	v_mov_b64_e32 v[26:27], v[10:11]
	v_mov_b64_e32 v[24:25], v[8:9]
	v_mov_b64_e32 v[22:23], v[6:7]
	v_mov_b64_e32 v[20:21], v[4:5]
	v_mov_b64_e32 v[18:19], v[2:3]
	v_mov_b64_e32 v[16:17], v[0:1]
	v_mov_b64_e32 v[92:93], v[12:13]
	v_mov_b64_e32 v[90:91], v[10:11]
	v_mov_b64_e32 v[88:89], v[8:9]
	v_mov_b64_e32 v[86:87], v[6:7]
	v_mov_b64_e32 v[84:85], v[4:5]
	v_mov_b64_e32 v[82:83], v[2:3]
	v_mov_b64_e32 v[80:81], v[0:1]
	v_mov_b64_e32 v[140:141], v[32:33]
	v_readfirstlane_b32 s5, v191
	v_readfirstlane_b32 s8, v192
	v_readfirstlane_b32 s2, v138
	v_readfirstlane_b32 s3, v139
	v_readfirstlane_b32 s10, v136
	v_readfirstlane_b32 s11, v137
	v_readfirstlane_b32 s0, v156
	v_and_b32_e32 v204, 7, v156
	v_bfe_u32 v205, v156, 4, 3
	v_xor_b32_e32 v205, v204, v205
	v_sub_u32_e32 v206, v205, v204
	v_lshlrev_b32_e32 v206, 4, v206
	v_subrev_u32_e32 v32, s2, v138
	v_subrev_u32_e32 v157, s10, v136
	v_add_u32_e32 v32, v32, v206
	v_add_u32_e32 v157, v157, v206
	v_lshrrev_b32_e32 v207, 3, v156
	v_lshlrev_b32_e32 v207, 7, v207
	v_lshl_add_u32 v207, v205, 4, v207
	v_and_b32_e32 v204, 31, v156
	v_bfe_u32 v205, v156, 5, 1
	v_bfe_u32 v206, v156, 1, 3
	v_lshlrev_b32_e32 v204, 7, v204
	v_add_u32_e32 v146, 0, v205
	v_xor_b32_e32 v146, v146, v206
	v_lshl_add_u32 v146, v146, 4, v204
	v_add_u32_e32 v147, 2, v205
	v_xor_b32_e32 v147, v147, v206
	v_lshl_add_u32 v147, v147, 4, v204
	v_add_u32_e32 v148, 4, v205
	v_xor_b32_e32 v148, v148, v206
	v_lshl_add_u32 v148, v148, 4, v204
	v_add_u32_e32 v149, 6, v205
	v_xor_b32_e32 v149, v149, v206
	v_lshl_add_u32 v149, v149, 4, v204
	s_lshr_b32 s0, s0, 6
	s_lshl_b32 s0, s0, 10
	s_add_i32 m0, s0, 16384
	s_nop 0
	global_load_lds_dwordx4 v32, s[2:3]
	s_add_i32 m0, s0, 24576
	s_nop 0
	global_load_lds_dwordx4 v157, s[10:11]
	s_add_u32 s2, s2, 0x68800
	s_addc_u32 s3, s3, 0
	s_add_u32 s10, s10, 0x2000
	s_addc_u32 s11, s11, 0
	s_waitcnt vmcnt(2)
	ds_write_b128 v207, v[120:123]
	ds_write_b128 v207, v[116:119] offset:8192
	s_waitcnt vmcnt(0) lgkmcnt(0)
	s_barrier
	ds_read_b128 v[166:169], v146
	ds_read_b128 v[170:173], v147
	v_mov_b32_e32 v158, 0
	v_mov_b32_e32 v159, 0
	v_mov_b32_e32 v160, 0
	v_mov_b32_e32 v161, 0
	v_mov_b32_e32 v162, 0
	v_mov_b32_e32 v163, 0
	v_mov_b32_e32 v164, 0
	v_mov_b32_e32 v165, 0
	v_mov_b32_e32 v150, 0
	v_mov_b32_e32 v151, 0
	s_mov_b32 s4, 0
	s_waitcnt lgkmcnt(0)
	v_mfma_f32_32x32x16_bf16 v[96:111], v[166:169], v[112:115], v[48:63]
	v_mfma_f32_32x32x16_bf16 v[96:111], v[170:173], v[42:45], v[96:111]
	ds_read_b128 v[166:169], v148
	ds_read_b128 v[170:173], v149
	v_mov_b32_e32 v174, 0
	v_mov_b32_e32 v175, 0
	v_mov_b32_e32 v176, 0
	v_mov_b32_e32 v177, 0
	v_mov_b32_e32 v178, 0
	v_mov_b32_e32 v179, 0
	v_mov_b32_e32 v180, 0
	v_mov_b32_e32 v181, 0
	v_mov_b32_e32 v182, 0
	v_mov_b32_e32 v183, 0
	v_mov_b32_e32 v184, 0
	v_mov_b32_e32 v185, 0
	v_mov_b32_e32 v186, 0
	v_mov_b32_e32 v187, 0
	v_mov_b32_e32 v188, 0
	v_mov_b32_e32 v189, 0
; DI float ex2(float x) { return __builtin_amdgcn_exp2f(x); }
; #define MFMA32(a, b, c) __builtin_amdgcn_mfma_f32_32x32x16_bf16((a), (b), (c), 0, 0, 0)
; template <int MODE>
; DI void attn_unit(unsigned char* lds, const AttnParams& ap, int b, int h, int qb, int tid) {
;     ...
;     for (int c = 0; c < NCH; ++c) { *(u32x4*)(Ks0 + (c * 64 + lrow) * 72 + 8 * lch) = kreg[c]; *(u32x4*)(Vs0 + (c * 64 + lrow) * 72 + 8 * lch) = vreg[c]; }
;     __syncthreads();
;     if (n + NCH < ntiles) {
; #pragma unroll
;       for (int c = 0; c < NCH; ++c) { const int jn = (MODE == 2) ? jb - NCH - c : jb + NCH + c; kreg[c] = *(const u32x4*)(kg + (size_t)jn * 64 * PLD); vreg[c] = *(const u32x4*)(vg + (size_t)jn * 4096); } }
; #pragma unroll
;     for (int c = 0; c < NCH; ++c) {
;     const int j = (MODE == 2) ? jb - c : jb + c;
;     const bf16_t* Ks = Ks0 + c * 64 * 72; const bf16_t* Vs = Vs0 + c * 64 * 72;
;     const bool active = (j <= cw) && (MODE != 0 || j >= cw - 8);
;     if (!active) continue;
;     if (MODE == 2 && D_EARLY && wdone) continue;
;     if (MODE == 1) {
; #pragma unroll
;       for (int kh = 0; kh < 2; ++kh) {
;         const bf16_t* kb = Ks + (32 * kh + r32) * 72 + 8 * hi;
;         bf16x8 p0[2], p1[2];
;         { f32x16 s0 = splat16(ap.negM);
;           s0 = MFMA32(*(const bf16x8*)(kb), qf[0], s0); s0 = MFMA32(*(const bf16x8*)(kb + 16), qf[1], s0);
; #pragma unroll
;           for (int i = 0; i < 16; ++i) { s0[i] = ex2(s0[i]); l0 += s0[i]; }
;           p0[0] = pack8(s0, 0); p0[1] = pack8(s0, 1); }
;         { f32x16 s1 = splat16(ap.negM);
;           s1 = MFMA32(*(const bf16x8*)(kb + 32), qf[2], s1); s1 = MFMA32(*(const bf16x8*)(kb + 48), qf[3], s1);
; #pragma unroll
;           for (int i = 0; i < 16; ++i) { s1[i] = ex2(s1[i]); l1 += s1[i]; }
;           p1[0] = pack8(s1, 0); p1[1] = pack8(s1, 1); }
; #pragma unroll
;         for (int kk = 0; kk < 2; ++kk) {
; #pragma unroll
;           for (int eb = 0; eb < 2; ++eb) { const bf16_t* vb = Vs + (32 * eb + r32) * 72 + 32 * kh + 16 * kk + 8 * hi; const bf16x8 vf = *(const bf16x8*)vb;
;             O0[eb] = MFMA32(vf, p0[kk], O0[eb]); O1[eb] = MFMA32(vf, p1[kk], O1[eb]); } }
;       }
.Lc_tile_ph0:
	s_add_i32 m0, s0, 32768
	s_nop 0
	global_load_lds_dwordx4 v32, s[2:3]
	s_add_i32 m0, s0, 40960
	s_nop 0
	global_load_lds_dwordx4 v157, s[10:11]
	s_add_u32 s2, s2, 0x68800
	s_addc_u32 s3, s3, 0
	s_add_u32 s10, s10, 0x2000
	s_addc_u32 s11, s11, 0
	s_waitcnt lgkmcnt(0)
	v_mfma_f32_32x32x16_bf16 v[116:131], v[166:169], v[38:41], v[48:63]
	v_exp_f32_e32 v96, v96
	v_exp_f32_e32 v97, v97
	v_exp_f32_e32 v98, v98
	v_exp_f32_e32 v99, v99
	v_mfma_f32_32x32x16_bf16 v[116:131], v[170:173], v[34:37], v[116:131]
	v_exp_f32_e32 v100, v100
	v_exp_f32_e32 v101, v101
	v_exp_f32_e32 v102, v102
	v_exp_f32_e32 v103, v103
	ds_read_b128 v[166:169], v146 offset:4096
	ds_read_b128 v[170:173], v147 offset:4096
	v_mfma_f32_32x32x16_bf16 v[80:95], v[174:177], v[158:161], v[80:95]
	v_exp_f32_e32 v104, v104
	v_exp_f32_e32 v105, v105
	v_add_f32_e32 v141, v141, v96
	v_add_f32_e32 v150, v150, v97
	v_add_f32_e32 v141, v141, v98
	v_add_f32_e32 v150, v150, v99
	v_mfma_f32_32x32x16_bf16 v[16:31], v[182:185], v[158:161], v[16:31]
	v_exp_f32_e32 v106, v106
	v_exp_f32_e32 v107, v107
	v_cvt_pk_bf16_f32 v158, v96, v97
	v_cvt_pk_bf16_f32 v159, v98, v99
	v_add_f32_e32 v141, v141, v100
	v_add_f32_e32 v150, v150, v101
	v_mfma_f32_32x32x16_bf16 v[80:95], v[178:181], v[162:165], v[80:95]
	v_exp_f32_e32 v108, v108
	v_exp_f32_e32 v109, v109
	v_cvt_pk_bf16_f32 v160, v100, v101
	v_cvt_pk_bf16_f32 v161, v102, v103
	v_add_f32_e32 v141, v141, v102
	v_add_f32_e32 v150, v150, v103
	v_mfma_f32_32x32x16_bf16 v[16:31], v[186:189], v[162:165], v[16:31]
	ds_read_b128 v[174:177], v146 offset:8192
	ds_read_b128 v[178:181], v147 offset:8192
	ds_read_b128 v[182:185], v146 offset:12288
	ds_read_b128 v[186:189], v147 offset:12288
	v_exp_f32_e32 v110, v110
	v_exp_f32_e32 v111, v111
	v_add_f32_e32 v141, v141, v104
	v_add_f32_e32 v150, v150, v105
	v_add_f32_e32 v141, v141, v106
	v_add_f32_e32 v150, v150, v107
	v_add_f32_e32 v141, v141, v108
	v_add_f32_e32 v150, v150, v109
	v_cvt_pk_bf16_f32 v162, v104, v105
	v_cvt_pk_bf16_f32 v163, v106, v107
	v_cvt_pk_bf16_f32 v164, v108, v109
	v_add_f32_e32 v141, v141, v110
	v_add_f32_e32 v150, v150, v111
	v_cvt_pk_bf16_f32 v165, v110, v111
	s_waitcnt lgkmcnt(0)
	v_mfma_f32_32x32x16_bf16 v[96:111], v[166:169], v[112:115], v[48:63]
	v_exp_f32_e32 v116, v116
	v_exp_f32_e32 v117, v117
	v_exp_f32_e32 v118, v118
	v_exp_f32_e32 v119, v119
	v_mfma_f32_32x32x16_bf16 v[96:111], v[170:173], v[42:45], v[96:111]
	v_exp_f32_e32 v120, v120
	v_exp_f32_e32 v121, v121
	v_exp_f32_e32 v122, v122
	v_exp_f32_e32 v123, v123
	ds_read_b128 v[166:169], v148 offset:4096
	ds_read_b128 v[170:173], v149 offset:4096
	v_mfma_f32_32x32x16_bf16 v[64:79], v[174:177], v[158:161], v[64:79]
	v_exp_f32_e32 v124, v124
	v_exp_f32_e32 v125, v125
	v_add_f32_e32 v140, v140, v116
	v_add_f32_e32 v151, v151, v117
	v_add_f32_e32 v140, v140, v118
	v_add_f32_e32 v151, v151, v119
	v_mfma_f32_32x32x16_bf16 v[0:15], v[182:185], v[158:161], v[0:15]
	v_exp_f32_e32 v126, v126
	v_exp_f32_e32 v127, v127
	v_cvt_pk_bf16_f32 v158, v116, v117
	v_cvt_pk_bf16_f32 v159, v118, v119
	v_add_f32_e32 v140, v140, v120
	v_add_f32_e32 v151, v151, v121
	v_mfma_f32_32x32x16_bf16 v[64:79], v[178:181], v[162:165], v[64:79]
	v_exp_f32_e32 v128, v128
	v_exp_f32_e32 v129, v129
	v_cvt_pk_bf16_f32 v160, v120, v121
	v_cvt_pk_bf16_f32 v161, v122, v123
	v_add_f32_e32 v140, v140, v122
	v_add_f32_e32 v151, v151, v123
	v_mfma_f32_32x32x16_bf16 v[0:15], v[186:189], v[162:165], v[0:15]
	v_exp_f32_e32 v130, v130
	v_exp_f32_e32 v131, v131
	v_add_f32_e32 v140, v140, v124
	v_add_f32_e32 v151, v151, v125
	v_add_f32_e32 v140, v140, v126
	v_add_f32_e32 v151, v151, v127
	v_add_f32_e32 v140, v140, v128
	v_add_f32_e32 v151, v151, v129
	v_cvt_pk_bf16_f32 v162, v124, v125
	v_cvt_pk_bf16_f32 v163, v126, v127
	v_cvt_pk_bf16_f32 v164, v128, v129
	v_add_f32_e32 v140, v140, v130
	v_add_f32_e32 v151, v151, v131
	v_cvt_pk_bf16_f32 v165, v130, v131
	s_waitcnt lgkmcnt(0)
	v_mfma_f32_32x32x16_bf16 v[116:131], v[166:169], v[38:41], v[48:63]
	v_exp_f32_e32 v96, v96
	v_exp_f32_e32 v97, v97
	v_exp_f32_e32 v98, v98
	v_exp_f32_e32 v99, v99
	v_mfma_f32_32x32x16_bf16 v[116:131], v[170:173], v[34:37], v[116:131]
	v_exp_f32_e32 v100, v100
	v_exp_f32_e32 v101, v101
	v_exp_f32_e32 v102, v102
	v_exp_f32_e32 v103, v103
	ds_read_b128 v[166:169], v146 offset:16384
	ds_read_b128 v[170:173], v147 offset:16384
	v_mfma_f32_32x32x16_bf16 v[80:95], v[174:177], v[158:161], v[80:95]
	v_exp_f32_e32 v104, v104
	v_exp_f32_e32 v105, v105
	v_add_f32_e32 v141, v141, v96
	v_add_f32_e32 v150, v150, v97
	v_add_f32_e32 v141, v141, v98
	v_add_f32_e32 v150, v150, v99
	v_mfma_f32_32x32x16_bf16 v[16:31], v[182:185], v[158:161], v[16:31]
	v_exp_f32_e32 v106, v106
	v_exp_f32_e32 v107, v107
	v_cvt_pk_bf16_f32 v158, v96, v97
	v_cvt_pk_bf16_f32 v159, v98, v99
	v_add_f32_e32 v141, v141, v100
	v_add_f32_e32 v150, v150, v101
	v_mfma_f32_32x32x16_bf16 v[80:95], v[178:181], v[162:165], v[80:95]
	v_exp_f32_e32 v108, v108
	v_exp_f32_e32 v109, v109
	v_cvt_pk_bf16_f32 v160, v100, v101
	v_cvt_pk_bf16_f32 v161, v102, v103
	v_add_f32_e32 v141, v141, v102
	v_add_f32_e32 v150, v150, v103
	v_mfma_f32_32x32x16_bf16 v[16:31], v[186:189], v[162:165], v[16:31]
	ds_read_b128 v[174:177], v148 offset:8192
	ds_read_b128 v[178:181], v149 offset:8192
	ds_read_b128 v[182:185], v148 offset:12288
	ds_read_b128 v[186:189], v149 offset:12288
	v_exp_f32_e32 v110, v110
	v_exp_f32_e32 v111, v111
	v_add_f32_e32 v141, v141, v104
	v_add_f32_e32 v150, v150, v105
	v_add_f32_e32 v141, v141, v106
	v_add_f32_e32 v150, v150, v107
	v_add_f32_e32 v141, v141, v108
	v_add_f32_e32 v150, v150, v109
	v_cvt_pk_bf16_f32 v162, v104, v105
	v_cvt_pk_bf16_f32 v163, v106, v107
	v_cvt_pk_bf16_f32 v164, v108, v109
	v_add_f32_e32 v141, v141, v110
	v_add_f32_e32 v150, v150, v111
	v_cvt_pk_bf16_f32 v165, v110, v111
	s_waitcnt lgkmcnt(0)
; DI float ex2(float x) { return __builtin_amdgcn_exp2f(x); }
; #define MFMA32(a, b, c) __builtin_amdgcn_mfma_f32_32x32x16_bf16((a), (b), (c), 0, 0, 0)
; template <int MODE>
; DI void attn_unit(unsigned char* lds, const AttnParams& ap, int b, int h, int qb, int tid) {
;     ...
;     for (int c = 0; c < NCH; ++c) { *(u32x4*)(Ks0 + (c * 64 + lrow) * 72 + 8 * lch) = kreg[c]; *(u32x4*)(Vs0 + (c * 64 + lrow) * 72 + 8 * lch) = vreg[c]; }
;     __syncthreads();
;     if (n + NCH < ntiles) {
; #pragma unroll
;       for (int c = 0; c < NCH; ++c) { const int jn = (MODE == 2) ? jb - NCH - c : jb + NCH + c; kreg[c] = *(const u32x4*)(kg + (size_t)jn * 64 * PLD); vreg[c] = *(const u32x4*)(vg + (size_t)jn * 4096); } }
; #pragma unroll
;     for (int c = 0; c < NCH; ++c) {
;     const int j = (MODE == 2) ? jb - c : jb + c;
;     const bf16_t* Ks = Ks0 + c * 64 * 72; const bf16_t* Vs = Vs0 + c * 64 * 72;
;     const bool active = (j <= cw) && (MODE != 0 || j >= cw - 8);
;     if (!active) continue;
;     if (MODE == 2 && D_EARLY && wdone) continue;
;     if (MODE == 1) {
; #pragma unroll
;       for (int kh = 0; kh < 2; ++kh) {
;         const bf16_t* kb = Ks + (32 * kh + r32) * 72 + 8 * hi;
;         bf16x8 p0[2], p1[2];
;         { f32x16 s0 = splat16(ap.negM);
;           s0 = MFMA32(*(const bf16x8*)(kb), qf[0], s0); s0 = MFMA32(*(const bf16x8*)(kb + 16), qf[1], s0);
; #pragma unroll
;           for (int i = 0; i < 16; ++i) { s0[i] = ex2(s0[i]); l0 += s0[i]; }
;           p0[0] = pack8(s0, 0); p0[1] = pack8(s0, 1); }
;         { f32x16 s1 = splat16(ap.negM);
;           s1 = MFMA32(*(const bf16x8*)(kb + 32), qf[2], s1); s1 = MFMA32(*(const bf16x8*)(kb + 48), qf[3], s1);
; #pragma unroll
;           for (int i = 0; i < 16; ++i) { s1[i] = ex2(s1[i]); l1 += s1[i]; }
;           p1[0] = pack8(s1, 0); p1[1] = pack8(s1, 1); }
; #pragma unroll
;         for (int kk = 0; kk < 2; ++kk) {
; #pragma unroll
;           for (int eb = 0; eb < 2; ++eb) { const bf16_t* vb = Vs + (32 * eb + r32) * 72 + 32 * kh + 16 * kk + 8 * hi; const bf16x8 vf = *(const bf16x8*)vb;
;             O0[eb] = MFMA32(vf, p0[kk], O0[eb]); O1[eb] = MFMA32(vf, p1[kk], O1[eb]); } }
;       }
	v_mfma_f32_32x32x16_bf16 v[96:111], v[166:169], v[112:115], v[48:63]
	v_exp_f32_e32 v116, v116
	v_exp_f32_e32 v117, v117
	v_exp_f32_e32 v118, v118
	v_exp_f32_e32 v119, v119
	v_mfma_f32_32x32x16_bf16 v[96:111], v[170:173], v[42:45], v[96:111]
	v_exp_f32_e32 v120, v120
	v_exp_f32_e32 v121, v121
	v_exp_f32_e32 v122, v122
	v_exp_f32_e32 v123, v123
	ds_read_b128 v[166:169], v148 offset:16384
	ds_read_b128 v[170:173], v149 offset:16384
	v_mfma_f32_32x32x16_bf16 v[64:79], v[174:177], v[158:161], v[64:79]
	v_exp_f32_e32 v124, v124
	v_exp_f32_e32 v125, v125
	v_add_f32_e32 v140, v140, v116
	v_add_f32_e32 v151, v151, v117
	v_add_f32_e32 v140, v140, v118
	v_add_f32_e32 v151, v151, v119
	v_mfma_f32_32x32x16_bf16 v[0:15], v[182:185], v[158:161], v[0:15]
	v_exp_f32_e32 v126, v126
	v_exp_f32_e32 v127, v127
	v_cvt_pk_bf16_f32 v158, v116, v117
	v_cvt_pk_bf16_f32 v159, v118, v119
	v_add_f32_e32 v140, v140, v120
	v_add_f32_e32 v151, v151, v121
	v_mfma_f32_32x32x16_bf16 v[64:79], v[178:181], v[162:165], v[64:79]
	v_exp_f32_e32 v128, v128
	v_exp_f32_e32 v129, v129
	v_cvt_pk_bf16_f32 v160, v120, v121
	v_cvt_pk_bf16_f32 v161, v122, v123
	v_add_f32_e32 v140, v140, v122
	v_add_f32_e32 v151, v151, v123
	v_mfma_f32_32x32x16_bf16 v[0:15], v[186:189], v[162:165], v[0:15]
	v_exp_f32_e32 v130, v130
	v_exp_f32_e32 v131, v131
	v_add_f32_e32 v140, v140, v124
	v_add_f32_e32 v151, v151, v125
	v_add_f32_e32 v140, v140, v126
	v_add_f32_e32 v151, v151, v127
	v_add_f32_e32 v140, v140, v128
	v_add_f32_e32 v151, v151, v129
	v_cvt_pk_bf16_f32 v162, v124, v125
	v_cvt_pk_bf16_f32 v163, v126, v127
	v_cvt_pk_bf16_f32 v164, v128, v129
	v_add_f32_e32 v140, v140, v130
	v_add_f32_e32 v151, v151, v131
	v_cvt_pk_bf16_f32 v165, v130, v131
	s_add_i32 s4, s4, 1
	s_waitcnt vmcnt(0) lgkmcnt(0)
	s_barrier
	s_nop 0
	s_barrier
	s_cmp_le_u32 s4, s5
	s_cbranch_scc1 .Lc_tile_ph1
	s_mov_b32 s9, 1
	s_branch .Lc_drain
.Lc_tile_ph1:
	s_add_i32 m0, s0, 0
	s_nop 0
	global_load_lds_dwordx4 v32, s[2:3]
	s_add_i32 m0, s0, 8192
	s_nop 0
	global_load_lds_dwordx4 v157, s[10:11]
	s_add_u32 s2, s2, 0x68800
	s_addc_u32 s3, s3, 0
	s_add_u32 s10, s10, 0x2000
	s_addc_u32 s11, s11, 0
	s_waitcnt lgkmcnt(0)
	v_mfma_f32_32x32x16_bf16 v[116:131], v[166:169], v[38:41], v[48:63]
	v_exp_f32_e32 v96, v96
	v_exp_f32_e32 v97, v97
	v_exp_f32_e32 v98, v98
	v_exp_f32_e32 v99, v99
	v_mfma_f32_32x32x16_bf16 v[116:131], v[170:173], v[34:37], v[116:131]
	v_exp_f32_e32 v100, v100
	v_exp_f32_e32 v101, v101
	v_exp_f32_e32 v102, v102
	v_exp_f32_e32 v103, v103
	ds_read_b128 v[166:169], v146 offset:20480
	ds_read_b128 v[170:173], v147 offset:20480
	v_mfma_f32_32x32x16_bf16 v[80:95], v[174:177], v[158:161], v[80:95]
	v_exp_f32_e32 v104, v104
	v_exp_f32_e32 v105, v105
	v_add_f32_e32 v141, v141, v96
	v_add_f32_e32 v150, v150, v97
	v_add_f32_e32 v141, v141, v98
	v_add_f32_e32 v150, v150, v99
	v_mfma_f32_32x32x16_bf16 v[16:31], v[182:185], v[158:161], v[16:31]
	v_exp_f32_e32 v106, v106
	v_exp_f32_e32 v107, v107
	v_cvt_pk_bf16_f32 v158, v96, v97
	v_cvt_pk_bf16_f32 v159, v98, v99
	v_add_f32_e32 v141, v141, v100
	v_add_f32_e32 v150, v150, v101
	v_mfma_f32_32x32x16_bf16 v[80:95], v[178:181], v[162:165], v[80:95]
	v_exp_f32_e32 v108, v108
	v_exp_f32_e32 v109, v109
	v_cvt_pk_bf16_f32 v160, v100, v101
	v_cvt_pk_bf16_f32 v161, v102, v103
	v_add_f32_e32 v141, v141, v102
	v_add_f32_e32 v150, v150, v103
	v_mfma_f32_32x32x16_bf16 v[16:31], v[186:189], v[162:165], v[16:31]
	ds_read_b128 v[174:177], v146 offset:24576
	ds_read_b128 v[178:181], v147 offset:24576
	ds_read_b128 v[182:185], v146 offset:28672
	ds_read_b128 v[186:189], v147 offset:28672
	v_exp_f32_e32 v110, v110
	v_exp_f32_e32 v111, v111
	v_add_f32_e32 v141, v141, v104
	v_add_f32_e32 v150, v150, v105
	v_add_f32_e32 v141, v141, v106
	v_add_f32_e32 v150, v150, v107
	v_add_f32_e32 v141, v141, v108
	v_add_f32_e32 v150, v150, v109
	v_cvt_pk_bf16_f32 v162, v104, v105
	v_cvt_pk_bf16_f32 v163, v106, v107
	v_cvt_pk_bf16_f32 v164, v108, v109
	v_add_f32_e32 v141, v141, v110
	v_add_f32_e32 v150, v150, v111
	v_cvt_pk_bf16_f32 v165, v110, v111
	s_waitcnt lgkmcnt(0)
	v_mfma_f32_32x32x16_bf16 v[96:111], v[166:169], v[112:115], v[48:63]
	v_exp_f32_e32 v116, v116
	v_exp_f32_e32 v117, v117
	v_exp_f32_e32 v118, v118
	v_exp_f32_e32 v119, v119
	v_mfma_f32_32x32x16_bf16 v[96:111], v[170:173], v[42:45], v[96:111]
	v_exp_f32_e32 v120, v120
	v_exp_f32_e32 v121, v121
	v_exp_f32_e32 v122, v122
	v_exp_f32_e32 v123, v123
	ds_read_b128 v[166:169], v148 offset:20480
	ds_read_b128 v[170:173], v149 offset:20480
	v_mfma_f32_32x32x16_bf16 v[64:79], v[174:177], v[158:161], v[64:79]
	v_exp_f32_e32 v124, v124
	v_exp_f32_e32 v125, v125
	v_add_f32_e32 v140, v140, v116
	v_add_f32_e32 v151, v151, v117
	v_add_f32_e32 v140, v140, v118
	v_add_f32_e32 v151, v151, v119
	v_mfma_f32_32x32x16_bf16 v[0:15], v[182:185], v[158:161], v[0:15]
	v_exp_f32_e32 v126, v126
	v_exp_f32_e32 v127, v127
	v_cvt_pk_bf16_f32 v158, v116, v117
	v_cvt_pk_bf16_f32 v159, v118, v119
	v_add_f32_e32 v140, v140, v120
	v_add_f32_e32 v151, v151, v121
	v_mfma_f32_32x32x16_bf16 v[64:79], v[178:181], v[162:165], v[64:79]
	v_exp_f32_e32 v128, v128
	v_exp_f32_e32 v129, v129
	v_cvt_pk_bf16_f32 v160, v120, v121
	v_cvt_pk_bf16_f32 v161, v122, v123
	v_add_f32_e32 v140, v140, v122
	v_add_f32_e32 v151, v151, v123
	v_mfma_f32_32x32x16_bf16 v[0:15], v[186:189], v[162:165], v[0:15]
	v_exp_f32_e32 v130, v130
	v_exp_f32_e32 v131, v131
	v_add_f32_e32 v140, v140, v124
	v_add_f32_e32 v151, v151, v125
	v_add_f32_e32 v140, v140, v126
	v_add_f32_e32 v151, v151, v127
	v_add_f32_e32 v140, v140, v128
	v_add_f32_e32 v151, v151, v129
	v_cvt_pk_bf16_f32 v162, v124, v125
	v_cvt_pk_bf16_f32 v163, v126, v127
	v_cvt_pk_bf16_f32 v164, v128, v129
	v_add_f32_e32 v140, v140, v130
	v_add_f32_e32 v151, v151, v131
	v_cvt_pk_bf16_f32 v165, v130, v131
	s_waitcnt lgkmcnt(0)
; DI float ex2(float x) { return __builtin_amdgcn_exp2f(x); }
; #define MFMA32(a, b, c) __builtin_amdgcn_mfma_f32_32x32x16_bf16((a), (b), (c), 0, 0, 0)
; template <int MODE>
; DI void attn_unit(unsigned char* lds, const AttnParams& ap, int b, int h, int qb, int tid) {
;     ...
;     for (int c = 0; c < NCH; ++c) { *(u32x4*)(Ks0 + (c * 64 + lrow) * 72 + 8 * lch) = kreg[c]; *(u32x4*)(Vs0 + (c * 64 + lrow) * 72 + 8 * lch) = vreg[c]; }
;     __syncthreads();
;     if (n + NCH < ntiles) {
; #pragma unroll
;       for (int c = 0; c < NCH; ++c) { const int jn = (MODE == 2) ? jb - NCH - c : jb + NCH + c; kreg[c] = *(const u32x4*)(kg + (size_t)jn * 64 * PLD); vreg[c] = *(const u32x4*)(vg + (size_t)jn * 4096); } }
;     ...
;       for (int kh = 0; kh < 2; ++kh) {
;         const bf16_t* kb = Ks + (32 * kh + r32) * 72 + 8 * hi;
;         bf16x8 p0[2], p1[2];
;         { f32x16 s0 = splat16(ap.negM);
;           s0 = MFMA32(*(const bf16x8*)(kb), qf[0], s0); s0 = MFMA32(*(const bf16x8*)(kb + 16), qf[1], s0);
; #pragma unroll
;           for (int i = 0; i < 16; ++i) { s0[i] = ex2(s0[i]); l0 += s0[i]; }
;           p0[0] = pack8(s0, 0); p0[1] = pack8(s0, 1); }
;         { f32x16 s1 = splat16(ap.negM);
;           s1 = MFMA32(*(const bf16x8*)(kb + 32), qf[2], s1); s1 = MFMA32(*(const bf16x8*)(kb + 48), qf[3], s1);
; #pragma unroll
;           for (int i = 0; i < 16; ++i) { s1[i] = ex2(s1[i]); l1 += s1[i]; }
;           p1[0] = pack8(s1, 0); p1[1] = pack8(s1, 1); }
; #pragma unroll
;         for (int kk = 0; kk < 2; ++kk) {
; #pragma unroll
;           for (int eb = 0; eb < 2; ++eb) { const bf16_t* vb = Vs + (32 * eb + r32) * 72 + 32 * kh + 16 * kk + 8 * hi; const bf16x8 vf = *(const bf16x8*)vb;
;             O0[eb] = MFMA32(vf, p0[kk], O0[eb]); O1[eb] = MFMA32(vf, p1[kk], O1[eb]); } }
	v_mfma_f32_32x32x16_bf16 v[116:131], v[166:169], v[38:41], v[48:63]
	v_exp_f32_e32 v96, v96
	v_exp_f32_e32 v97, v97
	v_exp_f32_e32 v98, v98
	v_exp_f32_e32 v99, v99
	v_mfma_f32_32x32x16_bf16 v[116:131], v[170:173], v[34:37], v[116:131]
	v_exp_f32_e32 v100, v100
	v_exp_f32_e32 v101, v101
	v_exp_f32_e32 v102, v102
	v_exp_f32_e32 v103, v103
	ds_read_b128 v[166:169], v146 offset:32768
	ds_read_b128 v[170:173], v147 offset:32768
	v_mfma_f32_32x32x16_bf16 v[80:95], v[174:177], v[158:161], v[80:95]
	v_exp_f32_e32 v104, v104
	v_exp_f32_e32 v105, v105
	v_add_f32_e32 v141, v141, v96
	v_add_f32_e32 v150, v150, v97
	v_add_f32_e32 v141, v141, v98
	v_add_f32_e32 v150, v150, v99
	v_mfma_f32_32x32x16_bf16 v[16:31], v[182:185], v[158:161], v[16:31]
	v_exp_f32_e32 v106, v106
	v_exp_f32_e32 v107, v107
	v_cvt_pk_bf16_f32 v158, v96, v97
	v_cvt_pk_bf16_f32 v159, v98, v99
	v_add_f32_e32 v141, v141, v100
	v_add_f32_e32 v150, v150, v101
	v_mfma_f32_32x32x16_bf16 v[80:95], v[178:181], v[162:165], v[80:95]
	v_exp_f32_e32 v108, v108
	v_exp_f32_e32 v109, v109
	v_cvt_pk_bf16_f32 v160, v100, v101
	v_cvt_pk_bf16_f32 v161, v102, v103
	v_add_f32_e32 v141, v141, v102
	v_add_f32_e32 v150, v150, v103
	v_mfma_f32_32x32x16_bf16 v[16:31], v[186:189], v[162:165], v[16:31]
	ds_read_b128 v[174:177], v148 offset:24576
	ds_read_b128 v[178:181], v149 offset:24576
	ds_read_b128 v[182:185], v148 offset:28672
	ds_read_b128 v[186:189], v149 offset:28672
	v_exp_f32_e32 v110, v110
	v_exp_f32_e32 v111, v111
	v_add_f32_e32 v141, v141, v104
	v_add_f32_e32 v150, v150, v105
	v_add_f32_e32 v141, v141, v106
	v_add_f32_e32 v150, v150, v107
	v_add_f32_e32 v141, v141, v108
	v_add_f32_e32 v150, v150, v109
	v_cvt_pk_bf16_f32 v162, v104, v105
	v_cvt_pk_bf16_f32 v163, v106, v107
	v_cvt_pk_bf16_f32 v164, v108, v109
	v_add_f32_e32 v141, v141, v110
	v_add_f32_e32 v150, v150, v111
	v_cvt_pk_bf16_f32 v165, v110, v111
	s_waitcnt lgkmcnt(0)
	v_mfma_f32_32x32x16_bf16 v[96:111], v[166:169], v[112:115], v[48:63]
	v_exp_f32_e32 v116, v116
	v_exp_f32_e32 v117, v117
	v_exp_f32_e32 v118, v118
	v_exp_f32_e32 v119, v119
	v_mfma_f32_32x32x16_bf16 v[96:111], v[170:173], v[42:45], v[96:111]
	v_exp_f32_e32 v120, v120
	v_exp_f32_e32 v121, v121
	v_exp_f32_e32 v122, v122
	v_exp_f32_e32 v123, v123
	ds_read_b128 v[166:169], v148 offset:32768
	ds_read_b128 v[170:173], v149 offset:32768
	v_mfma_f32_32x32x16_bf16 v[64:79], v[174:177], v[158:161], v[64:79]
	v_exp_f32_e32 v124, v124
	v_exp_f32_e32 v125, v125
	v_add_f32_e32 v140, v140, v116
	v_add_f32_e32 v151, v151, v117
	v_add_f32_e32 v140, v140, v118
	v_add_f32_e32 v151, v151, v119
	v_mfma_f32_32x32x16_bf16 v[0:15], v[182:185], v[158:161], v[0:15]
	v_exp_f32_e32 v126, v126
	v_exp_f32_e32 v127, v127
	v_cvt_pk_bf16_f32 v158, v116, v117
	v_cvt_pk_bf16_f32 v159, v118, v119
	v_add_f32_e32 v140, v140, v120
	v_add_f32_e32 v151, v151, v121
	v_mfma_f32_32x32x16_bf16 v[64:79], v[178:181], v[162:165], v[64:79]
	v_exp_f32_e32 v128, v128
	v_exp_f32_e32 v129, v129
	v_cvt_pk_bf16_f32 v160, v120, v121
	v_cvt_pk_bf16_f32 v161, v122, v123
	v_add_f32_e32 v140, v140, v122
	v_add_f32_e32 v151, v151, v123
	v_mfma_f32_32x32x16_bf16 v[0:15], v[186:189], v[162:165], v[0:15]
	v_exp_f32_e32 v130, v130
	v_exp_f32_e32 v131, v131
	v_add_f32_e32 v140, v140, v124
	v_add_f32_e32 v151, v151, v125
	v_add_f32_e32 v140, v140, v126
	v_add_f32_e32 v151, v151, v127
	v_add_f32_e32 v140, v140, v128
	v_add_f32_e32 v151, v151, v129
	v_cvt_pk_bf16_f32 v162, v124, v125
	v_cvt_pk_bf16_f32 v163, v126, v127
	v_cvt_pk_bf16_f32 v164, v128, v129
	v_add_f32_e32 v140, v140, v130
	v_add_f32_e32 v151, v151, v131
	v_cvt_pk_bf16_f32 v165, v130, v131
	s_add_i32 s4, s4, 1
	s_waitcnt vmcnt(0) lgkmcnt(0)
	s_barrier
	s_nop 0
	s_barrier
	s_cmp_le_u32 s4, s5
	s_cbranch_scc1 .Lc_tile_ph2
	s_mov_b32 s9, 2
	s_branch .Lc_drain
.Lc_tile_ph2:
	s_add_i32 m0, s0, 16384
	s_nop 0
	global_load_lds_dwordx4 v32, s[2:3]
	s_add_i32 m0, s0, 24576
	s_nop 0
	global_load_lds_dwordx4 v157, s[10:11]
	s_add_u32 s2, s2, 0x68800
	s_addc_u32 s3, s3, 0
	s_add_u32 s10, s10, 0x2000
	s_addc_u32 s11, s11, 0
	s_waitcnt lgkmcnt(0)
	v_mfma_f32_32x32x16_bf16 v[116:131], v[166:169], v[38:41], v[48:63]
	v_exp_f32_e32 v96, v96
	v_exp_f32_e32 v97, v97
	v_exp_f32_e32 v98, v98
	v_exp_f32_e32 v99, v99
	v_mfma_f32_32x32x16_bf16 v[116:131], v[170:173], v[34:37], v[116:131]
	v_exp_f32_e32 v100, v100
	v_exp_f32_e32 v101, v101
	v_exp_f32_e32 v102, v102
	v_exp_f32_e32 v103, v103
	ds_read_b128 v[166:169], v146 offset:36864
	ds_read_b128 v[170:173], v147 offset:36864
	v_mfma_f32_32x32x16_bf16 v[80:95], v[174:177], v[158:161], v[80:95]
	v_exp_f32_e32 v104, v104
	v_exp_f32_e32 v105, v105
	v_add_f32_e32 v141, v141, v96
	v_add_f32_e32 v150, v150, v97
	v_add_f32_e32 v141, v141, v98
	v_add_f32_e32 v150, v150, v99
	v_mfma_f32_32x32x16_bf16 v[16:31], v[182:185], v[158:161], v[16:31]
	v_exp_f32_e32 v106, v106
	v_exp_f32_e32 v107, v107
	v_cvt_pk_bf16_f32 v158, v96, v97
	v_cvt_pk_bf16_f32 v159, v98, v99
	v_add_f32_e32 v141, v141, v100
	v_add_f32_e32 v150, v150, v101
	v_mfma_f32_32x32x16_bf16 v[80:95], v[178:181], v[162:165], v[80:95]
	v_exp_f32_e32 v108, v108
	v_exp_f32_e32 v109, v109
	v_cvt_pk_bf16_f32 v160, v100, v101
	v_cvt_pk_bf16_f32 v161, v102, v103
	v_add_f32_e32 v141, v141, v102
	v_add_f32_e32 v150, v150, v103
	v_mfma_f32_32x32x16_bf16 v[16:31], v[186:189], v[162:165], v[16:31]
	ds_read_b128 v[174:177], v146 offset:40960
	ds_read_b128 v[178:181], v147 offset:40960
	ds_read_b128 v[182:185], v146 offset:45056
	ds_read_b128 v[186:189], v147 offset:45056
	v_exp_f32_e32 v110, v110
	v_exp_f32_e32 v111, v111
	v_add_f32_e32 v141, v141, v104
	v_add_f32_e32 v150, v150, v105
	v_add_f32_e32 v141, v141, v106
	v_add_f32_e32 v150, v150, v107
	v_add_f32_e32 v141, v141, v108
	v_add_f32_e32 v150, v150, v109
	v_cvt_pk_bf16_f32 v162, v104, v105
	v_cvt_pk_bf16_f32 v163, v106, v107
	v_cvt_pk_bf16_f32 v164, v108, v109
	v_add_f32_e32 v141, v141, v110
	v_add_f32_e32 v150, v150, v111
	v_cvt_pk_bf16_f32 v165, v110, v111
	s_waitcnt lgkmcnt(0)
; DI float ex2(float x) { return __builtin_amdgcn_exp2f(x); }
; #define MFMA32(a, b, c) __builtin_amdgcn_mfma_f32_32x32x16_bf16((a), (b), (c), 0, 0, 0)
; template <int MODE>
; DI void attn_unit(unsigned char* lds, const AttnParams& ap, int b, int h, int qb, int tid) {
;     ...
;     for (int c = 0; c < NCH; ++c) { *(u32x4*)(Ks0 + (c * 64 + lrow) * 72 + 8 * lch) = kreg[c]; *(u32x4*)(Vs0 + (c * 64 + lrow) * 72 + 8 * lch) = vreg[c]; }
;     __syncthreads();
;     if (n + NCH < ntiles) {
; #pragma unroll
;       for (int c = 0; c < NCH; ++c) { const int jn = (MODE == 2) ? jb - NCH - c : jb + NCH + c; kreg[c] = *(const u32x4*)(kg + (size_t)jn * 64 * PLD); vreg[c] = *(const u32x4*)(vg + (size_t)jn * 4096); } }
;     ...
;       for (int kh = 0; kh < 2; ++kh) {
;         const bf16_t* kb = Ks + (32 * kh + r32) * 72 + 8 * hi;
;         bf16x8 p0[2], p1[2];
;         { f32x16 s0 = splat16(ap.negM);
;           s0 = MFMA32(*(const bf16x8*)(kb), qf[0], s0); s0 = MFMA32(*(const bf16x8*)(kb + 16), qf[1], s0);
; #pragma unroll
;           for (int i = 0; i < 16; ++i) { s0[i] = ex2(s0[i]); l0 += s0[i]; }
;           p0[0] = pack8(s0, 0); p0[1] = pack8(s0, 1); }
;         { f32x16 s1 = splat16(ap.negM);
;           s1 = MFMA32(*(const bf16x8*)(kb + 32), qf[2], s1); s1 = MFMA32(*(const bf16x8*)(kb + 48), qf[3], s1);
; #pragma unroll
;           for (int i = 0; i < 16; ++i) { s1[i] = ex2(s1[i]); l1 += s1[i]; }
;           p1[0] = pack8(s1, 0); p1[1] = pack8(s1, 1); }
; #pragma unroll
;         for (int kk = 0; kk < 2; ++kk) {
; #pragma unroll
;           for (int eb = 0; eb < 2; ++eb) { const bf16_t* vb = Vs + (32 * eb + r32) * 72 + 32 * kh + 16 * kk + 8 * hi; const bf16x8 vf = *(const bf16x8*)vb;
;             O0[eb] = MFMA32(vf, p0[kk], O0[eb]); O1[eb] = MFMA32(vf, p1[kk], O1[eb]); } }
	v_mfma_f32_32x32x16_bf16 v[96:111], v[166:169], v[112:115], v[48:63]
	v_exp_f32_e32 v116, v116
	v_exp_f32_e32 v117, v117
	v_exp_f32_e32 v118, v118
	v_exp_f32_e32 v119, v119
	v_mfma_f32_32x32x16_bf16 v[96:111], v[170:173], v[42:45], v[96:111]
	v_exp_f32_e32 v120, v120
	v_exp_f32_e32 v121, v121
	v_exp_f32_e32 v122, v122
	v_exp_f32_e32 v123, v123
	ds_read_b128 v[166:169], v148 offset:36864
	ds_read_b128 v[170:173], v149 offset:36864
	v_mfma_f32_32x32x16_bf16 v[64:79], v[174:177], v[158:161], v[64:79]
	v_exp_f32_e32 v124, v124
	v_exp_f32_e32 v125, v125
	v_add_f32_e32 v140, v140, v116
	v_add_f32_e32 v151, v151, v117
	v_add_f32_e32 v140, v140, v118
	v_add_f32_e32 v151, v151, v119
	v_mfma_f32_32x32x16_bf16 v[0:15], v[182:185], v[158:161], v[0:15]
	v_exp_f32_e32 v126, v126
	v_exp_f32_e32 v127, v127
	v_cvt_pk_bf16_f32 v158, v116, v117
	v_cvt_pk_bf16_f32 v159, v118, v119
	v_add_f32_e32 v140, v140, v120
	v_add_f32_e32 v151, v151, v121
	v_mfma_f32_32x32x16_bf16 v[64:79], v[178:181], v[162:165], v[64:79]
	v_exp_f32_e32 v128, v128
	v_exp_f32_e32 v129, v129
	v_cvt_pk_bf16_f32 v160, v120, v121
	v_cvt_pk_bf16_f32 v161, v122, v123
	v_add_f32_e32 v140, v140, v122
	v_add_f32_e32 v151, v151, v123
	v_mfma_f32_32x32x16_bf16 v[0:15], v[186:189], v[162:165], v[0:15]
	v_exp_f32_e32 v130, v130
	v_exp_f32_e32 v131, v131
	v_add_f32_e32 v140, v140, v124
	v_add_f32_e32 v151, v151, v125
	v_add_f32_e32 v140, v140, v126
	v_add_f32_e32 v151, v151, v127
	v_add_f32_e32 v140, v140, v128
	v_add_f32_e32 v151, v151, v129
	v_cvt_pk_bf16_f32 v162, v124, v125
	v_cvt_pk_bf16_f32 v163, v126, v127
	v_cvt_pk_bf16_f32 v164, v128, v129
	v_add_f32_e32 v140, v140, v130
	v_add_f32_e32 v151, v151, v131
	v_cvt_pk_bf16_f32 v165, v130, v131
	s_waitcnt lgkmcnt(0)
	v_mfma_f32_32x32x16_bf16 v[116:131], v[166:169], v[38:41], v[48:63]
	v_exp_f32_e32 v96, v96
	v_exp_f32_e32 v97, v97
	v_exp_f32_e32 v98, v98
	v_exp_f32_e32 v99, v99
	v_mfma_f32_32x32x16_bf16 v[116:131], v[170:173], v[34:37], v[116:131]
	v_exp_f32_e32 v100, v100
	v_exp_f32_e32 v101, v101
	v_exp_f32_e32 v102, v102
	v_exp_f32_e32 v103, v103
	ds_read_b128 v[166:169], v146
	ds_read_b128 v[170:173], v147
	v_mfma_f32_32x32x16_bf16 v[80:95], v[174:177], v[158:161], v[80:95]
	v_exp_f32_e32 v104, v104
	v_exp_f32_e32 v105, v105
	v_add_f32_e32 v141, v141, v96
	v_add_f32_e32 v150, v150, v97
	v_add_f32_e32 v141, v141, v98
	v_add_f32_e32 v150, v150, v99
	v_mfma_f32_32x32x16_bf16 v[16:31], v[182:185], v[158:161], v[16:31]
	v_exp_f32_e32 v106, v106
	v_exp_f32_e32 v107, v107
	v_cvt_pk_bf16_f32 v158, v96, v97
	v_cvt_pk_bf16_f32 v159, v98, v99
	v_add_f32_e32 v141, v141, v100
	v_add_f32_e32 v150, v150, v101
	v_mfma_f32_32x32x16_bf16 v[80:95], v[178:181], v[162:165], v[80:95]
	v_exp_f32_e32 v108, v108
	v_exp_f32_e32 v109, v109
	v_cvt_pk_bf16_f32 v160, v100, v101
	v_cvt_pk_bf16_f32 v161, v102, v103
	v_add_f32_e32 v141, v141, v102
	v_add_f32_e32 v150, v150, v103
	v_mfma_f32_32x32x16_bf16 v[16:31], v[186:189], v[162:165], v[16:31]
	ds_read_b128 v[174:177], v148 offset:40960
	ds_read_b128 v[178:181], v149 offset:40960
	ds_read_b128 v[182:185], v148 offset:45056
	ds_read_b128 v[186:189], v149 offset:45056
	v_exp_f32_e32 v110, v110
	v_exp_f32_e32 v111, v111
	v_add_f32_e32 v141, v141, v104
	v_add_f32_e32 v150, v150, v105
	v_add_f32_e32 v141, v141, v106
	v_add_f32_e32 v150, v150, v107
	v_add_f32_e32 v141, v141, v108
	v_add_f32_e32 v150, v150, v109
	v_cvt_pk_bf16_f32 v162, v104, v105
	v_cvt_pk_bf16_f32 v163, v106, v107
	v_cvt_pk_bf16_f32 v164, v108, v109
	v_add_f32_e32 v141, v141, v110
	v_add_f32_e32 v150, v150, v111
	v_cvt_pk_bf16_f32 v165, v110, v111
	s_waitcnt lgkmcnt(0)
	v_mfma_f32_32x32x16_bf16 v[96:111], v[166:169], v[112:115], v[48:63]
	v_exp_f32_e32 v116, v116
	v_exp_f32_e32 v117, v117
	v_exp_f32_e32 v118, v118
	v_exp_f32_e32 v119, v119
	v_mfma_f32_32x32x16_bf16 v[96:111], v[170:173], v[42:45], v[96:111]
	v_exp_f32_e32 v120, v120
	v_exp_f32_e32 v121, v121
	v_exp_f32_e32 v122, v122
	v_exp_f32_e32 v123, v123
	ds_read_b128 v[166:169], v148
	ds_read_b128 v[170:173], v149
	v_mfma_f32_32x32x16_bf16 v[64:79], v[174:177], v[158:161], v[64:79]
	v_exp_f32_e32 v124, v124
	v_exp_f32_e32 v125, v125
	v_add_f32_e32 v140, v140, v116
	v_add_f32_e32 v151, v151, v117
	v_add_f32_e32 v140, v140, v118
	v_add_f32_e32 v151, v151, v119
	v_mfma_f32_32x32x16_bf16 v[0:15], v[182:185], v[158:161], v[0:15]
	v_exp_f32_e32 v126, v126
	v_exp_f32_e32 v127, v127
	v_cvt_pk_bf16_f32 v158, v116, v117
	v_cvt_pk_bf16_f32 v159, v118, v119
	v_add_f32_e32 v140, v140, v120
	v_add_f32_e32 v151, v151, v121
	v_mfma_f32_32x32x16_bf16 v[64:79], v[178:181], v[162:165], v[64:79]
	v_exp_f32_e32 v128, v128
	v_exp_f32_e32 v129, v129
	v_cvt_pk_bf16_f32 v160, v120, v121
	v_cvt_pk_bf16_f32 v161, v122, v123
	v_add_f32_e32 v140, v140, v122
	v_add_f32_e32 v151, v151, v123
	v_mfma_f32_32x32x16_bf16 v[0:15], v[186:189], v[162:165], v[0:15]
	v_exp_f32_e32 v130, v130
	v_exp_f32_e32 v131, v131
	v_add_f32_e32 v140, v140, v124
	v_add_f32_e32 v151, v151, v125
	v_add_f32_e32 v140, v140, v126
	v_add_f32_e32 v151, v151, v127
	v_add_f32_e32 v140, v140, v128
	v_add_f32_e32 v151, v151, v129
	v_cvt_pk_bf16_f32 v162, v124, v125
	v_cvt_pk_bf16_f32 v163, v126, v127
	v_cvt_pk_bf16_f32 v164, v128, v129
	v_add_f32_e32 v140, v140, v130
	v_add_f32_e32 v151, v151, v131
	v_cvt_pk_bf16_f32 v165, v130, v131
	s_add_i32 s4, s4, 1
	s_waitcnt vmcnt(0) lgkmcnt(0)
	s_barrier
	s_nop 0
	s_barrier
	s_cmp_le_u32 s4, s5
	s_cbranch_scc1 .Lc_tile_ph0
	s_mov_b32 s9, 0

; template <int MODE>
; DI void attn_unit(unsigned char* lds, const AttnParams& ap, int b, int h, int qb, int tid) {
;     ...
;   for (int n = 0; n < ntiles; n += NCH) {
;     const int jb = (MODE == 2) ? jhi - n : jlo + n;
;     __syncthreads();
;     if (MODE == 2 && D_EARLY) { int alld = 1;
; #pragma unroll
;       for (int w = 0; w < 8; ++w) alld &= flags[w];
;       if (alld) break; }
; #pragma unroll
;     for (int c = 0; c < NCH; ++c) { *(u32x4*)(Ks0 + (c * 64 + lrow) * 72 + 8 * lch) = kreg[c]; *(u32x4*)(Vs0 + (c * 64 + lrow) * 72 + 8 * lch) = vreg[c]; }
;     __syncthreads();
;     if (n + NCH < ntiles) {
; #pragma unroll
;       for (int c = 0; c < NCH; ++c) { const int jn = (MODE == 2) ? jb - NCH - c : jb + NCH + c; kreg[c] = *(const u32x4*)(kg + (size_t)jn * 64 * PLD); vreg[c] = *(const u32x4*)(vg + (size_t)jn * 4096); } }
;     ...
;     const bool active = (j <= cw) && (MODE != 0 || j >= cw - 8);
;     if (!active) continue;
.Lc_idle_ph0:
	s_add_i32 m0, s0, 32768
	s_nop 0
	global_load_lds_dwordx4 v32, s[2:3]
	s_add_i32 m0, s0, 40960
	s_nop 0
	global_load_lds_dwordx4 v157, s[10:11]
	s_add_u32 s2, s2, 0x68800
	s_addc_u32 s3, s3, 0
	s_add_u32 s10, s10, 0x2000
	s_addc_u32 s11, s11, 0
	s_add_i32 s4, s4, 1
	s_waitcnt vmcnt(0) lgkmcnt(0)
	s_barrier
	s_nop 0
	s_barrier
	s_cmp_gt_u32 s4, s8
	s_cbranch_scc1 .Lc_tiles_done
.Lc_idle_ph1:
	s_add_i32 m0, s0, 0
	s_nop 0
	global_load_lds_dwordx4 v32, s[2:3]
	s_add_i32 m0, s0, 8192
	s_nop 0
	global_load_lds_dwordx4 v157, s[10:11]
	s_add_u32 s2, s2, 0x68800
	s_addc_u32 s3, s3, 0
	s_add_u32 s10, s10, 0x2000
	s_addc_u32 s11, s11, 0
	s_add_i32 s4, s4, 1
	s_waitcnt vmcnt(0) lgkmcnt(0)
	s_barrier
	s_nop 0
	s_barrier
	s_cmp_gt_u32 s4, s8
	s_cbranch_scc1 .Lc_tiles_done
.Lc_idle_ph2:
	s_add_i32 m0, s0, 16384
	s_nop 0
	global_load_lds_dwordx4 v32, s[2:3]
	s_add_i32 m0, s0, 24576
	s_nop 0
	global_load_lds_dwordx4 v157, s[10:11]
	s_add_u32 s2, s2, 0x68800
	s_addc_u32 s3, s3, 0
	s_add_u32 s10, s10, 0x2000
	s_addc_u32 s11, s11, 0
	s_add_i32 s4, s4, 1
	s_waitcnt vmcnt(0) lgkmcnt(0)
	s_barrier
	s_nop 0
	s_barrier
	s_cmp_gt_u32 s4, s8
	s_cbranch_scc1 .Lc_tiles_done
	s_branch .Lc_idle_ph0
